# v44 + P7 K-loop MFMA order: leading half accumulator pairs along a boustrophedon path (pair turns share an operand), trailing half boustrophedon k0 then reversed k1
# speedup vs baseline: 1.0220x; 1.0039x over previous
.LBB0_793:
	ds_read_b128 v[144:147], v153
	ds_read_b128 v[158:161], v153 offset:1024
	ds_read_b128 v[162:165], v153 offset:2048
	ds_read_b128 v[166:169], v153 offset:3072
	ds_read_b128 v[170:173], v154
	ds_read_b128 v[176:179], v154 offset:1024
	ds_read_b128 v[180:183], v154 offset:2048
	ds_read_b128 v[184:187], v154 offset:3072
	s_add_u32 s44, s42, 0xfff80080
	s_addc_u32 s45, s43, -1
	s_cmp_eq_u32 s65, 28
	s_cselect_b32 s47, s35, s45
	s_cselect_b32 s46, s61, s44
	s_cselect_b32 s45, s27, s64
	s_cselect_b32 s44, s62, s63
	s_add_u32 s100, s46, 0x80
	s_addc_u32 s101, s47, 0
	s_add_i32 m0, s10, 0xc000
	ds_read_b128 v[188:191], v155
	ds_read_b128 v[192:195], v155 offset:1024
	ds_read_b128 v[196:199], v155 offset:2048
	ds_read_b128 v[200:203], v155 offset:3072
	ds_read_b128 v[204:207], v155 offset:4096
	ds_read_b128 v[208:211], v155 offset:5120
	ds_read_b128 v[212:215], v155 offset:6144
	ds_read_b128 v[216:219], v155 offset:7168
	global_load_lds_dwordx4 v136, s[42:43]
	s_add_i32 m0, s10, 0xe000
	s_nop 0
	global_load_lds_dwordx4 v138, s[42:43]
	s_waitcnt vmcnt(8)
	s_waitcnt lgkmcnt(0)
	s_setprio 1
	s_waitcnt lgkmcnt(0)
	v_mfma_f32_16x16x32_bf16 v[124:127], v[144:147], v[188:191], v[124:127]
	v_mfma_f32_16x16x32_bf16 v[124:127], v[158:161], v[192:195], v[124:127]
	v_mfma_f32_16x16x32_bf16 v[120:123], v[166:169], v[192:195], v[120:123]
	v_mfma_f32_16x16x32_bf16 v[120:123], v[162:165], v[188:191], v[120:123]
	v_mfma_f32_16x16x32_bf16 v[104:107], v[162:165], v[196:199], v[104:107]
	v_mfma_f32_16x16x32_bf16 v[104:107], v[166:169], v[200:203], v[104:107]
	v_mfma_f32_16x16x32_bf16 v[108:111], v[158:161], v[200:203], v[108:111]
	v_mfma_f32_16x16x32_bf16 v[108:111], v[144:147], v[196:199], v[108:111]
	v_mfma_f32_16x16x32_bf16 v[92:95], v[144:147], v[204:207], v[92:95]
	v_mfma_f32_16x16x32_bf16 v[92:95], v[158:161], v[208:211], v[92:95]
	v_mfma_f32_16x16x32_bf16 v[88:91], v[166:169], v[208:211], v[88:91]
	v_mfma_f32_16x16x32_bf16 v[88:91], v[162:165], v[204:207], v[88:91]
	v_mfma_f32_16x16x32_bf16 v[72:75], v[162:165], v[212:215], v[72:75]
	v_mfma_f32_16x16x32_bf16 v[72:75], v[166:169], v[216:219], v[72:75]
	v_mfma_f32_16x16x32_bf16 v[76:79], v[158:161], v[216:219], v[76:79]
	v_mfma_f32_16x16x32_bf16 v[76:79], v[144:147], v[212:215], v[76:79]
	s_setprio 0
	s_setprio 1
	v_mfma_f32_16x16x32_bf16 v[116:119], v[170:173], v[188:191], v[116:119]
	v_mfma_f32_16x16x32_bf16 v[116:119], v[176:179], v[192:195], v[116:119]
	v_mfma_f32_16x16x32_bf16 v[112:115], v[184:187], v[192:195], v[112:115]
	v_mfma_f32_16x16x32_bf16 v[112:115], v[180:183], v[188:191], v[112:115]
	v_mfma_f32_16x16x32_bf16 v[96:99], v[180:183], v[196:199], v[96:99]
	v_mfma_f32_16x16x32_bf16 v[96:99], v[184:187], v[200:203], v[96:99]
	v_mfma_f32_16x16x32_bf16 v[100:103], v[176:179], v[200:203], v[100:103]
	v_mfma_f32_16x16x32_bf16 v[100:103], v[170:173], v[196:199], v[100:103]
	v_mfma_f32_16x16x32_bf16 v[84:87], v[170:173], v[204:207], v[84:87]
	v_mfma_f32_16x16x32_bf16 v[84:87], v[176:179], v[208:211], v[84:87]
	v_mfma_f32_16x16x32_bf16 v[80:83], v[184:187], v[208:211], v[80:83]
	v_mfma_f32_16x16x32_bf16 v[80:83], v[180:183], v[204:207], v[80:83]
	v_mfma_f32_16x16x32_bf16 v[64:67], v[180:183], v[212:215], v[64:67]
	v_mfma_f32_16x16x32_bf16 v[64:67], v[184:187], v[216:219], v[64:67]
	v_mfma_f32_16x16x32_bf16 v[68:71], v[176:179], v[216:219], v[68:71]
	v_mfma_f32_16x16x32_bf16 v[68:71], v[170:173], v[212:215], v[68:71]
	s_setprio 0
	s_barrier
	s_add_i32 s66, s49, s0
	s_mov_b32 m0, s66
	ds_read_b128 v[188:191], v155 offset:16384
	ds_read_b128 v[192:195], v155 offset:17408
	ds_read_b128 v[196:199], v155 offset:18432
	ds_read_b128 v[200:203], v155 offset:19456
	ds_read_b128 v[204:207], v155 offset:20480
	ds_read_b128 v[208:211], v155 offset:21504
	ds_read_b128 v[212:215], v155 offset:22528
	ds_read_b128 v[216:219], v155 offset:23552
	global_load_lds_dwordx4 v132, s[44:45]
	s_add_i32 m0, s66, 0x2000
	s_add_u32 s66, s44, 0x80000
	s_addc_u32 s67, s45, 0
	s_add_i32 s68, s50, s0
	global_load_lds_dwordx4 v128, s[44:45]
	s_mov_b32 m0, s68
	s_nop 0
	global_load_lds_dwordx4 v132, s[66:67]
	s_add_i32 m0, s68, 0x2000
	s_nop 0
	global_load_lds_dwordx4 v128, s[66:67]
	s_mov_b32 m0, s10
	s_nop 0
	global_load_lds_dwordx4 v134, s[46:47]
	s_mov_b32 m0, s11
	s_nop 0
	global_load_lds_dwordx4 v130, s[46:47]
	s_waitcnt vmcnt(8)
	s_waitcnt lgkmcnt(0)
	s_setprio 1
	s_waitcnt lgkmcnt(0)
	v_mfma_f32_16x16x32_bf16 v[60:63], v[144:147], v[188:191], v[60:63]
	v_mfma_f32_16x16x32_bf16 v[60:63], v[158:161], v[192:195], v[60:63]
	v_mfma_f32_16x16x32_bf16 v[56:59], v[166:169], v[192:195], v[56:59]
	v_mfma_f32_16x16x32_bf16 v[56:59], v[162:165], v[188:191], v[56:59]
	v_mfma_f32_16x16x32_bf16 v[40:43], v[162:165], v[196:199], v[40:43]
	v_mfma_f32_16x16x32_bf16 v[40:43], v[166:169], v[200:203], v[40:43]
	v_mfma_f32_16x16x32_bf16 v[44:47], v[158:161], v[200:203], v[44:47]
	v_mfma_f32_16x16x32_bf16 v[44:47], v[144:147], v[196:199], v[44:47]
	v_mfma_f32_16x16x32_bf16 v[28:31], v[144:147], v[204:207], v[28:31]
	v_mfma_f32_16x16x32_bf16 v[28:31], v[158:161], v[208:211], v[28:31]
	v_mfma_f32_16x16x32_bf16 v[24:27], v[166:169], v[208:211], v[24:27]
	v_mfma_f32_16x16x32_bf16 v[24:27], v[162:165], v[204:207], v[24:27]
	v_mfma_f32_16x16x32_bf16 v[8:11], v[162:165], v[212:215], v[8:11]
	v_mfma_f32_16x16x32_bf16 v[8:11], v[166:169], v[216:219], v[8:11]
	v_mfma_f32_16x16x32_bf16 v[12:15], v[158:161], v[216:219], v[12:15]
	v_mfma_f32_16x16x32_bf16 v[12:15], v[144:147], v[212:215], v[12:15]
	s_setprio 0
	s_setprio 1
	v_mfma_f32_16x16x32_bf16 v[52:55], v[170:173], v[188:191], v[52:55]
	v_mfma_f32_16x16x32_bf16 v[52:55], v[176:179], v[192:195], v[52:55]
	v_mfma_f32_16x16x32_bf16 v[48:51], v[184:187], v[192:195], v[48:51]
	v_mfma_f32_16x16x32_bf16 v[48:51], v[180:183], v[188:191], v[48:51]
	v_mfma_f32_16x16x32_bf16 v[32:35], v[180:183], v[196:199], v[32:35]
	v_mfma_f32_16x16x32_bf16 v[32:35], v[184:187], v[200:203], v[32:35]
	v_mfma_f32_16x16x32_bf16 v[36:39], v[176:179], v[200:203], v[36:39]
	v_mfma_f32_16x16x32_bf16 v[36:39], v[170:173], v[196:199], v[36:39]
	v_mfma_f32_16x16x32_bf16 v[20:23], v[170:173], v[204:207], v[20:23]
	v_mfma_f32_16x16x32_bf16 v[20:23], v[176:179], v[208:211], v[20:23]
	v_mfma_f32_16x16x32_bf16 v[16:19], v[184:187], v[208:211], v[16:19]
	v_mfma_f32_16x16x32_bf16 v[16:19], v[180:183], v[204:207], v[16:19]
	v_mfma_f32_16x16x32_bf16 v[0:3], v[180:183], v[212:215], v[0:3]
	v_mfma_f32_16x16x32_bf16 v[0:3], v[184:187], v[216:219], v[0:3]
	v_mfma_f32_16x16x32_bf16 v[4:7], v[176:179], v[216:219], v[4:7]
	v_mfma_f32_16x16x32_bf16 v[4:7], v[170:173], v[212:215], v[4:7]
	s_setprio 0
	s_barrier
	s_add_i32 s66, 0, 0x18000
	v_add_u32_e32 v157, s66, v151
	s_add_i32 s67, 0, 0x1c000
	ds_read_b128 v[144:147], v157
	ds_read_b128 v[158:161], v157 offset:1024
	ds_read_b128 v[162:165], v157 offset:2048
	ds_read_b128 v[166:169], v157 offset:3072
	v_add_u32_e32 v157, s67, v151
	ds_read_b128 v[170:173], v157
	ds_read_b128 v[176:179], v157 offset:1024
	ds_read_b128 v[180:183], v157 offset:2048
	ds_read_b128 v[184:187], v157 offset:3072
	s_add_u32 s46, s46, 0x80000
	s_addc_u32 s47, s47, 0
	s_mov_b32 m0, s14
	ds_read_b128 v[188:191], v155 offset:32768
	ds_read_b128 v[192:195], v155 offset:33792
	ds_read_b128 v[196:199], v155 offset:34816
	ds_read_b128 v[200:203], v155 offset:35840
	ds_read_b128 v[204:207], v155 offset:36864
	ds_read_b128 v[208:211], v155 offset:37888
	ds_read_b128 v[212:215], v155 offset:38912
	ds_read_b128 v[216:219], v155 offset:39936
	global_load_lds_dwordx4 v134, s[46:47]
	s_mov_b32 m0, s15
	s_nop 0
	global_load_lds_dwordx4 v130, s[46:47]
	s_waitcnt vmcnt(8)
	s_waitcnt lgkmcnt(0)
	s_setprio 1
	s_waitcnt lgkmcnt(0)
	v_mfma_f32_16x16x32_bf16 v[124:127], v[144:147], v[188:191], v[124:127]
	v_mfma_f32_16x16x32_bf16 v[124:127], v[158:161], v[192:195], v[124:127]
	v_mfma_f32_16x16x32_bf16 v[120:123], v[166:169], v[192:195], v[120:123]
	v_mfma_f32_16x16x32_bf16 v[120:123], v[162:165], v[188:191], v[120:123]
	v_mfma_f32_16x16x32_bf16 v[104:107], v[162:165], v[196:199], v[104:107]
	v_mfma_f32_16x16x32_bf16 v[104:107], v[166:169], v[200:203], v[104:107]
	v_mfma_f32_16x16x32_bf16 v[108:111], v[158:161], v[200:203], v[108:111]
	v_mfma_f32_16x16x32_bf16 v[108:111], v[144:147], v[196:199], v[108:111]
	v_mfma_f32_16x16x32_bf16 v[92:95], v[144:147], v[204:207], v[92:95]
	v_mfma_f32_16x16x32_bf16 v[92:95], v[158:161], v[208:211], v[92:95]
	v_mfma_f32_16x16x32_bf16 v[88:91], v[166:169], v[208:211], v[88:91]
	v_mfma_f32_16x16x32_bf16 v[88:91], v[162:165], v[204:207], v[88:91]
	v_mfma_f32_16x16x32_bf16 v[72:75], v[162:165], v[212:215], v[72:75]
	v_mfma_f32_16x16x32_bf16 v[72:75], v[166:169], v[216:219], v[72:75]
	v_mfma_f32_16x16x32_bf16 v[76:79], v[158:161], v[216:219], v[76:79]
	v_mfma_f32_16x16x32_bf16 v[76:79], v[144:147], v[212:215], v[76:79]
	s_setprio 0
	s_setprio 1
	v_mfma_f32_16x16x32_bf16 v[116:119], v[170:173], v[188:191], v[116:119]
	v_mfma_f32_16x16x32_bf16 v[116:119], v[176:179], v[192:195], v[116:119]
	v_mfma_f32_16x16x32_bf16 v[112:115], v[184:187], v[192:195], v[112:115]
	v_mfma_f32_16x16x32_bf16 v[112:115], v[180:183], v[188:191], v[112:115]
	v_mfma_f32_16x16x32_bf16 v[96:99], v[180:183], v[196:199], v[96:99]
	v_mfma_f32_16x16x32_bf16 v[96:99], v[184:187], v[200:203], v[96:99]
	v_mfma_f32_16x16x32_bf16 v[100:103], v[176:179], v[200:203], v[100:103]
	v_mfma_f32_16x16x32_bf16 v[100:103], v[170:173], v[196:199], v[100:103]
	v_mfma_f32_16x16x32_bf16 v[84:87], v[170:173], v[204:207], v[84:87]
	v_mfma_f32_16x16x32_bf16 v[84:87], v[176:179], v[208:211], v[84:87]
	v_mfma_f32_16x16x32_bf16 v[80:83], v[184:187], v[208:211], v[80:83]
	v_mfma_f32_16x16x32_bf16 v[80:83], v[180:183], v[204:207], v[80:83]
	v_mfma_f32_16x16x32_bf16 v[64:67], v[180:183], v[212:215], v[64:67]
	v_mfma_f32_16x16x32_bf16 v[64:67], v[184:187], v[216:219], v[64:67]
	v_mfma_f32_16x16x32_bf16 v[68:71], v[176:179], v[216:219], v[68:71]
	v_mfma_f32_16x16x32_bf16 v[68:71], v[170:173], v[212:215], v[68:71]
	s_setprio 0
	s_barrier
	s_add_i32 s46, s66, s0
	s_add_u32 s98, s44, 0x80
	s_addc_u32 s99, s45, 0
	s_mov_b32 m0, s46
	ds_read_b128 v[188:191], v155 offset:49152
	ds_read_b128 v[192:195], v155 offset:50176
	ds_read_b128 v[196:199], v155 offset:51200
	ds_read_b128 v[200:203], v155 offset:52224
	ds_read_b128 v[204:207], v155 offset:53248
	ds_read_b128 v[208:211], v155 offset:54272
	ds_read_b128 v[212:215], v155 offset:55296
	ds_read_b128 v[216:219], v155 offset:56320
	global_load_lds_dwordx4 v132, s[98:99]
	s_add_i32 m0, s46, 0x2000
	s_add_u32 s44, s44, 0x80080
	s_addc_u32 s45, s45, 0
	s_add_i32 s46, s67, s0
	global_load_lds_dwordx4 v128, s[98:99]
	s_mov_b32 m0, s46
	s_nop 0
	global_load_lds_dwordx4 v132, s[44:45]
	s_add_i32 m0, s46, 0x2000
	s_nop 0
	global_load_lds_dwordx4 v128, s[44:45]
	s_mov_b32 m0, s41
	s_nop 0
	global_load_lds_dwordx4 v134, s[100:101]
	s_mov_b32 m0, s48
	s_nop 0
	global_load_lds_dwordx4 v130, s[100:101]
	s_waitcnt vmcnt(8)
	s_waitcnt lgkmcnt(0)
	s_setprio 1
	s_waitcnt lgkmcnt(0)
	v_mfma_f32_16x16x32_bf16 v[60:63], v[144:147], v[188:191], v[60:63]
	v_mfma_f32_16x16x32_bf16 v[60:63], v[158:161], v[192:195], v[60:63]
	v_mfma_f32_16x16x32_bf16 v[56:59], v[166:169], v[192:195], v[56:59]
	v_mfma_f32_16x16x32_bf16 v[56:59], v[162:165], v[188:191], v[56:59]
	v_mfma_f32_16x16x32_bf16 v[40:43], v[162:165], v[196:199], v[40:43]
	v_mfma_f32_16x16x32_bf16 v[40:43], v[166:169], v[200:203], v[40:43]
	v_mfma_f32_16x16x32_bf16 v[44:47], v[158:161], v[200:203], v[44:47]
	v_mfma_f32_16x16x32_bf16 v[44:47], v[144:147], v[196:199], v[44:47]
	v_mfma_f32_16x16x32_bf16 v[28:31], v[144:147], v[204:207], v[28:31]
	v_mfma_f32_16x16x32_bf16 v[28:31], v[158:161], v[208:211], v[28:31]
	v_mfma_f32_16x16x32_bf16 v[24:27], v[166:169], v[208:211], v[24:27]
	v_mfma_f32_16x16x32_bf16 v[24:27], v[162:165], v[204:207], v[24:27]
	v_mfma_f32_16x16x32_bf16 v[8:11], v[162:165], v[212:215], v[8:11]
	v_mfma_f32_16x16x32_bf16 v[8:11], v[166:169], v[216:219], v[8:11]
	v_mfma_f32_16x16x32_bf16 v[12:15], v[158:161], v[216:219], v[12:15]
	v_mfma_f32_16x16x32_bf16 v[12:15], v[144:147], v[212:215], v[12:15]
	s_setprio 0
	s_setprio 1
	v_mfma_f32_16x16x32_bf16 v[52:55], v[170:173], v[188:191], v[52:55]
	v_mfma_f32_16x16x32_bf16 v[52:55], v[176:179], v[192:195], v[52:55]
	v_mfma_f32_16x16x32_bf16 v[48:51], v[184:187], v[192:195], v[48:51]
	v_mfma_f32_16x16x32_bf16 v[48:51], v[180:183], v[188:191], v[48:51]
	v_mfma_f32_16x16x32_bf16 v[32:35], v[180:183], v[196:199], v[32:35]
	v_mfma_f32_16x16x32_bf16 v[32:35], v[184:187], v[200:203], v[32:35]
	v_mfma_f32_16x16x32_bf16 v[36:39], v[176:179], v[200:203], v[36:39]
	v_mfma_f32_16x16x32_bf16 v[36:39], v[170:173], v[196:199], v[36:39]
	v_mfma_f32_16x16x32_bf16 v[20:23], v[170:173], v[204:207], v[20:23]
	v_mfma_f32_16x16x32_bf16 v[20:23], v[176:179], v[208:211], v[20:23]
	v_mfma_f32_16x16x32_bf16 v[16:19], v[184:187], v[208:211], v[16:19]
	v_mfma_f32_16x16x32_bf16 v[16:19], v[180:183], v[204:207], v[16:19]
	v_mfma_f32_16x16x32_bf16 v[0:3], v[180:183], v[212:215], v[0:3]
	v_mfma_f32_16x16x32_bf16 v[0:3], v[184:187], v[216:219], v[0:3]
	v_mfma_f32_16x16x32_bf16 v[4:7], v[176:179], v[216:219], v[4:7]
	v_mfma_f32_16x16x32_bf16 v[4:7], v[170:173], v[212:215], v[4:7]
	s_setprio 0
	s_barrier
	s_add_i32 s65, s65, 2
	s_add_u32 s42, s42, 0x100
	s_addc_u32 s43, s43, 0
	s_add_u32 s63, s63, 0x100
	s_addc_u32 s64, s64, 0
	s_cmp_gt_u32 s65, 29
	s_cbranch_scc0 .LBB0_793
	s_branch .Lp7_kloop_done
.Lp7_kloop_h1:
	ds_read_b128 v[144:147], v153
	ds_read_b128 v[158:161], v153 offset:1024
	ds_read_b128 v[162:165], v153 offset:2048
	ds_read_b128 v[166:169], v153 offset:3072
	ds_read_b128 v[170:173], v154
	ds_read_b128 v[176:179], v154 offset:1024
	ds_read_b128 v[180:183], v154 offset:2048
	ds_read_b128 v[184:187], v154 offset:3072
	s_add_u32 s44, s42, 0xfff80080
	s_addc_u32 s45, s43, -1
	s_cmp_eq_u32 s65, 28
	s_cselect_b32 s47, s35, s45
	s_cselect_b32 s46, s61, s44
	s_cselect_b32 s45, s27, s64
	s_cselect_b32 s44, s62, s63
	s_add_u32 s100, s46, 0x80
	s_addc_u32 s101, s47, 0
	s_add_i32 m0, s10, 0xc000
	ds_read_b128 v[188:191], v155
	ds_read_b128 v[192:195], v155 offset:1024
	ds_read_b128 v[196:199], v155 offset:2048
	ds_read_b128 v[200:203], v155 offset:3072
	ds_read_b128 v[204:207], v155 offset:4096
	ds_read_b128 v[208:211], v155 offset:5120
	ds_read_b128 v[212:215], v155 offset:6144
	ds_read_b128 v[216:219], v155 offset:7168
	global_load_lds_dwordx4 v136, s[42:43]
	s_add_i32 m0, s10, 0xe000
	s_nop 0
	global_load_lds_dwordx4 v138, s[42:43]
	s_waitcnt vmcnt(8)
	s_waitcnt lgkmcnt(0)
	s_barrier
	s_setprio 2
	s_waitcnt lgkmcnt(0)
	v_mfma_f32_16x16x32_bf16 v[124:127], v[144:147], v[188:191], v[124:127]
	v_mfma_f32_16x16x32_bf16 v[120:123], v[162:165], v[188:191], v[120:123]
	v_mfma_f32_16x16x32_bf16 v[104:107], v[162:165], v[196:199], v[104:107]
	v_mfma_f32_16x16x32_bf16 v[108:111], v[144:147], v[196:199], v[108:111]
	v_mfma_f32_16x16x32_bf16 v[92:95], v[144:147], v[204:207], v[92:95]
	v_mfma_f32_16x16x32_bf16 v[88:91], v[162:165], v[204:207], v[88:91]
	v_mfma_f32_16x16x32_bf16 v[72:75], v[162:165], v[212:215], v[72:75]
	v_mfma_f32_16x16x32_bf16 v[76:79], v[144:147], v[212:215], v[76:79]
	v_mfma_f32_16x16x32_bf16 v[76:79], v[158:161], v[216:219], v[76:79]
	v_mfma_f32_16x16x32_bf16 v[72:75], v[166:169], v[216:219], v[72:75]
	v_mfma_f32_16x16x32_bf16 v[88:91], v[166:169], v[208:211], v[88:91]
	v_mfma_f32_16x16x32_bf16 v[92:95], v[158:161], v[208:211], v[92:95]
	v_mfma_f32_16x16x32_bf16 v[108:111], v[158:161], v[200:203], v[108:111]
	v_mfma_f32_16x16x32_bf16 v[104:107], v[166:169], v[200:203], v[104:107]
	v_mfma_f32_16x16x32_bf16 v[120:123], v[166:169], v[192:195], v[120:123]
	v_mfma_f32_16x16x32_bf16 v[124:127], v[158:161], v[192:195], v[124:127]
	s_setprio 0
	s_setprio 2
	v_mfma_f32_16x16x32_bf16 v[116:119], v[170:173], v[188:191], v[116:119]
	v_mfma_f32_16x16x32_bf16 v[112:115], v[180:183], v[188:191], v[112:115]
	v_mfma_f32_16x16x32_bf16 v[96:99], v[180:183], v[196:199], v[96:99]
	v_mfma_f32_16x16x32_bf16 v[100:103], v[170:173], v[196:199], v[100:103]
	v_mfma_f32_16x16x32_bf16 v[84:87], v[170:173], v[204:207], v[84:87]
	v_mfma_f32_16x16x32_bf16 v[80:83], v[180:183], v[204:207], v[80:83]
	v_mfma_f32_16x16x32_bf16 v[64:67], v[180:183], v[212:215], v[64:67]
	v_mfma_f32_16x16x32_bf16 v[68:71], v[170:173], v[212:215], v[68:71]
	v_mfma_f32_16x16x32_bf16 v[68:71], v[176:179], v[216:219], v[68:71]
	v_mfma_f32_16x16x32_bf16 v[64:67], v[184:187], v[216:219], v[64:67]
	v_mfma_f32_16x16x32_bf16 v[80:83], v[184:187], v[208:211], v[80:83]
	v_mfma_f32_16x16x32_bf16 v[84:87], v[176:179], v[208:211], v[84:87]
	v_mfma_f32_16x16x32_bf16 v[100:103], v[176:179], v[200:203], v[100:103]
	v_mfma_f32_16x16x32_bf16 v[96:99], v[184:187], v[200:203], v[96:99]
	v_mfma_f32_16x16x32_bf16 v[112:115], v[184:187], v[192:195], v[112:115]
	v_mfma_f32_16x16x32_bf16 v[116:119], v[176:179], v[192:195], v[116:119]
	s_setprio 0
	s_add_i32 s66, s49, s0
	s_mov_b32 m0, s66
	ds_read_b128 v[188:191], v155 offset:16384
	ds_read_b128 v[192:195], v155 offset:17408
	ds_read_b128 v[196:199], v155 offset:18432
	ds_read_b128 v[200:203], v155 offset:19456
	ds_read_b128 v[204:207], v155 offset:20480
	ds_read_b128 v[208:211], v155 offset:21504
	ds_read_b128 v[212:215], v155 offset:22528
	ds_read_b128 v[216:219], v155 offset:23552
	global_load_lds_dwordx4 v132, s[44:45]
	s_add_i32 m0, s66, 0x2000
	s_add_u32 s66, s44, 0x80000
	s_addc_u32 s67, s45, 0
	s_add_i32 s68, s50, s0
	global_load_lds_dwordx4 v128, s[44:45]
	s_mov_b32 m0, s68
	s_nop 0
	global_load_lds_dwordx4 v132, s[66:67]
	s_add_i32 m0, s68, 0x2000
	s_nop 0
	global_load_lds_dwordx4 v128, s[66:67]
	s_mov_b32 m0, s10
	s_nop 0
	global_load_lds_dwordx4 v134, s[46:47]
	s_mov_b32 m0, s11
	s_nop 0
	global_load_lds_dwordx4 v130, s[46:47]
	s_waitcnt vmcnt(8)
	s_waitcnt lgkmcnt(0)
	s_barrier
	s_setprio 2
	s_waitcnt lgkmcnt(0)
	v_mfma_f32_16x16x32_bf16 v[60:63], v[144:147], v[188:191], v[60:63]
	v_mfma_f32_16x16x32_bf16 v[56:59], v[162:165], v[188:191], v[56:59]
	v_mfma_f32_16x16x32_bf16 v[40:43], v[162:165], v[196:199], v[40:43]
	v_mfma_f32_16x16x32_bf16 v[44:47], v[144:147], v[196:199], v[44:47]
	v_mfma_f32_16x16x32_bf16 v[28:31], v[144:147], v[204:207], v[28:31]
	v_mfma_f32_16x16x32_bf16 v[24:27], v[162:165], v[204:207], v[24:27]
	v_mfma_f32_16x16x32_bf16 v[8:11], v[162:165], v[212:215], v[8:11]
	v_mfma_f32_16x16x32_bf16 v[12:15], v[144:147], v[212:215], v[12:15]
	v_mfma_f32_16x16x32_bf16 v[12:15], v[158:161], v[216:219], v[12:15]
	v_mfma_f32_16x16x32_bf16 v[8:11], v[166:169], v[216:219], v[8:11]
	v_mfma_f32_16x16x32_bf16 v[24:27], v[166:169], v[208:211], v[24:27]
	v_mfma_f32_16x16x32_bf16 v[28:31], v[158:161], v[208:211], v[28:31]
	v_mfma_f32_16x16x32_bf16 v[44:47], v[158:161], v[200:203], v[44:47]
	v_mfma_f32_16x16x32_bf16 v[40:43], v[166:169], v[200:203], v[40:43]
	v_mfma_f32_16x16x32_bf16 v[56:59], v[166:169], v[192:195], v[56:59]
	v_mfma_f32_16x16x32_bf16 v[60:63], v[158:161], v[192:195], v[60:63]
	s_setprio 0
	s_setprio 2
	v_mfma_f32_16x16x32_bf16 v[52:55], v[170:173], v[188:191], v[52:55]
	v_mfma_f32_16x16x32_bf16 v[48:51], v[180:183], v[188:191], v[48:51]
	v_mfma_f32_16x16x32_bf16 v[32:35], v[180:183], v[196:199], v[32:35]
	v_mfma_f32_16x16x32_bf16 v[36:39], v[170:173], v[196:199], v[36:39]
	v_mfma_f32_16x16x32_bf16 v[20:23], v[170:173], v[204:207], v[20:23]
	v_mfma_f32_16x16x32_bf16 v[16:19], v[180:183], v[204:207], v[16:19]
	v_mfma_f32_16x16x32_bf16 v[0:3], v[180:183], v[212:215], v[0:3]
	v_mfma_f32_16x16x32_bf16 v[4:7], v[170:173], v[212:215], v[4:7]
	v_mfma_f32_16x16x32_bf16 v[4:7], v[176:179], v[216:219], v[4:7]
	v_mfma_f32_16x16x32_bf16 v[0:3], v[184:187], v[216:219], v[0:3]
	v_mfma_f32_16x16x32_bf16 v[16:19], v[184:187], v[208:211], v[16:19]
	v_mfma_f32_16x16x32_bf16 v[20:23], v[176:179], v[208:211], v[20:23]
	v_mfma_f32_16x16x32_bf16 v[36:39], v[176:179], v[200:203], v[36:39]
	v_mfma_f32_16x16x32_bf16 v[32:35], v[184:187], v[200:203], v[32:35]
	v_mfma_f32_16x16x32_bf16 v[48:51], v[184:187], v[192:195], v[48:51]
	v_mfma_f32_16x16x32_bf16 v[52:55], v[176:179], v[192:195], v[52:55]
	s_setprio 0
	s_add_i32 s66, 0, 0x18000
	v_add_u32_e32 v157, s66, v151
	s_add_i32 s67, 0, 0x1c000
	ds_read_b128 v[144:147], v157
	ds_read_b128 v[158:161], v157 offset:1024
	ds_read_b128 v[162:165], v157 offset:2048
	ds_read_b128 v[166:169], v157 offset:3072
	v_add_u32_e32 v157, s67, v151
	ds_read_b128 v[170:173], v157
	ds_read_b128 v[176:179], v157 offset:1024
	ds_read_b128 v[180:183], v157 offset:2048
	ds_read_b128 v[184:187], v157 offset:3072
	s_add_u32 s46, s46, 0x80000
	s_addc_u32 s47, s47, 0
	s_mov_b32 m0, s14
	ds_read_b128 v[188:191], v155 offset:32768
	ds_read_b128 v[192:195], v155 offset:33792
	ds_read_b128 v[196:199], v155 offset:34816
	ds_read_b128 v[200:203], v155 offset:35840
	ds_read_b128 v[204:207], v155 offset:36864
	ds_read_b128 v[208:211], v155 offset:37888
	ds_read_b128 v[212:215], v155 offset:38912
	ds_read_b128 v[216:219], v155 offset:39936
	global_load_lds_dwordx4 v134, s[46:47]
	s_mov_b32 m0, s15
	s_nop 0
	global_load_lds_dwordx4 v130, s[46:47]
	s_waitcnt vmcnt(8)
	s_waitcnt lgkmcnt(0)
	s_barrier
	s_setprio 2
	s_waitcnt lgkmcnt(0)
	v_mfma_f32_16x16x32_bf16 v[124:127], v[144:147], v[188:191], v[124:127]
	v_mfma_f32_16x16x32_bf16 v[120:123], v[162:165], v[188:191], v[120:123]
	v_mfma_f32_16x16x32_bf16 v[104:107], v[162:165], v[196:199], v[104:107]
	v_mfma_f32_16x16x32_bf16 v[108:111], v[144:147], v[196:199], v[108:111]
	v_mfma_f32_16x16x32_bf16 v[92:95], v[144:147], v[204:207], v[92:95]
	v_mfma_f32_16x16x32_bf16 v[88:91], v[162:165], v[204:207], v[88:91]
	v_mfma_f32_16x16x32_bf16 v[72:75], v[162:165], v[212:215], v[72:75]
	v_mfma_f32_16x16x32_bf16 v[76:79], v[144:147], v[212:215], v[76:79]
	v_mfma_f32_16x16x32_bf16 v[76:79], v[158:161], v[216:219], v[76:79]
	v_mfma_f32_16x16x32_bf16 v[72:75], v[166:169], v[216:219], v[72:75]
	v_mfma_f32_16x16x32_bf16 v[88:91], v[166:169], v[208:211], v[88:91]
	v_mfma_f32_16x16x32_bf16 v[92:95], v[158:161], v[208:211], v[92:95]
	v_mfma_f32_16x16x32_bf16 v[108:111], v[158:161], v[200:203], v[108:111]
	v_mfma_f32_16x16x32_bf16 v[104:107], v[166:169], v[200:203], v[104:107]
	v_mfma_f32_16x16x32_bf16 v[120:123], v[166:169], v[192:195], v[120:123]
	v_mfma_f32_16x16x32_bf16 v[124:127], v[158:161], v[192:195], v[124:127]
	s_setprio 0
	s_setprio 2
	v_mfma_f32_16x16x32_bf16 v[116:119], v[170:173], v[188:191], v[116:119]
	v_mfma_f32_16x16x32_bf16 v[112:115], v[180:183], v[188:191], v[112:115]
	v_mfma_f32_16x16x32_bf16 v[96:99], v[180:183], v[196:199], v[96:99]
	v_mfma_f32_16x16x32_bf16 v[100:103], v[170:173], v[196:199], v[100:103]
	v_mfma_f32_16x16x32_bf16 v[84:87], v[170:173], v[204:207], v[84:87]
	v_mfma_f32_16x16x32_bf16 v[80:83], v[180:183], v[204:207], v[80:83]
	v_mfma_f32_16x16x32_bf16 v[64:67], v[180:183], v[212:215], v[64:67]
	v_mfma_f32_16x16x32_bf16 v[68:71], v[170:173], v[212:215], v[68:71]
	v_mfma_f32_16x16x32_bf16 v[68:71], v[176:179], v[216:219], v[68:71]
	v_mfma_f32_16x16x32_bf16 v[64:67], v[184:187], v[216:219], v[64:67]
	v_mfma_f32_16x16x32_bf16 v[80:83], v[184:187], v[208:211], v[80:83]
	v_mfma_f32_16x16x32_bf16 v[84:87], v[176:179], v[208:211], v[84:87]
	v_mfma_f32_16x16x32_bf16 v[100:103], v[176:179], v[200:203], v[100:103]
	v_mfma_f32_16x16x32_bf16 v[96:99], v[184:187], v[200:203], v[96:99]
	v_mfma_f32_16x16x32_bf16 v[112:115], v[184:187], v[192:195], v[112:115]
	v_mfma_f32_16x16x32_bf16 v[116:119], v[176:179], v[192:195], v[116:119]
	s_setprio 0
	s_add_i32 s46, s66, s0
	s_add_u32 s98, s44, 0x80
	s_addc_u32 s99, s45, 0
	s_mov_b32 m0, s46
	ds_read_b128 v[188:191], v155 offset:49152
	ds_read_b128 v[192:195], v155 offset:50176
	ds_read_b128 v[196:199], v155 offset:51200
	ds_read_b128 v[200:203], v155 offset:52224
	ds_read_b128 v[204:207], v155 offset:53248
	ds_read_b128 v[208:211], v155 offset:54272
	ds_read_b128 v[212:215], v155 offset:55296
	ds_read_b128 v[216:219], v155 offset:56320
	global_load_lds_dwordx4 v132, s[98:99]
	s_add_i32 m0, s46, 0x2000
	s_add_u32 s44, s44, 0x80080
	s_addc_u32 s45, s45, 0
	s_add_i32 s46, s67, s0
	global_load_lds_dwordx4 v128, s[98:99]
	s_mov_b32 m0, s46
	s_nop 0
	global_load_lds_dwordx4 v132, s[44:45]
	s_add_i32 m0, s46, 0x2000
	s_nop 0
	global_load_lds_dwordx4 v128, s[44:45]
	s_mov_b32 m0, s41
	s_nop 0
	global_load_lds_dwordx4 v134, s[100:101]
	s_mov_b32 m0, s48
	s_nop 0
	global_load_lds_dwordx4 v130, s[100:101]
	s_waitcnt vmcnt(8)
	s_waitcnt lgkmcnt(0)
	s_barrier
	s_setprio 2
	s_waitcnt lgkmcnt(0)
	v_mfma_f32_16x16x32_bf16 v[60:63], v[144:147], v[188:191], v[60:63]
	v_mfma_f32_16x16x32_bf16 v[56:59], v[162:165], v[188:191], v[56:59]
	v_mfma_f32_16x16x32_bf16 v[40:43], v[162:165], v[196:199], v[40:43]
	v_mfma_f32_16x16x32_bf16 v[44:47], v[144:147], v[196:199], v[44:47]
	v_mfma_f32_16x16x32_bf16 v[28:31], v[144:147], v[204:207], v[28:31]
	v_mfma_f32_16x16x32_bf16 v[24:27], v[162:165], v[204:207], v[24:27]
	v_mfma_f32_16x16x32_bf16 v[8:11], v[162:165], v[212:215], v[8:11]
	v_mfma_f32_16x16x32_bf16 v[12:15], v[144:147], v[212:215], v[12:15]
	v_mfma_f32_16x16x32_bf16 v[12:15], v[158:161], v[216:219], v[12:15]
	v_mfma_f32_16x16x32_bf16 v[8:11], v[166:169], v[216:219], v[8:11]
	v_mfma_f32_16x16x32_bf16 v[24:27], v[166:169], v[208:211], v[24:27]
	v_mfma_f32_16x16x32_bf16 v[28:31], v[158:161], v[208:211], v[28:31]
	v_mfma_f32_16x16x32_bf16 v[44:47], v[158:161], v[200:203], v[44:47]
	v_mfma_f32_16x16x32_bf16 v[40:43], v[166:169], v[200:203], v[40:43]
	v_mfma_f32_16x16x32_bf16 v[56:59], v[166:169], v[192:195], v[56:59]
	v_mfma_f32_16x16x32_bf16 v[60:63], v[158:161], v[192:195], v[60:63]
	s_setprio 0
	s_setprio 2
	v_mfma_f32_16x16x32_bf16 v[52:55], v[170:173], v[188:191], v[52:55]
	v_mfma_f32_16x16x32_bf16 v[48:51], v[180:183], v[188:191], v[48:51]
	v_mfma_f32_16x16x32_bf16 v[32:35], v[180:183], v[196:199], v[32:35]
	v_mfma_f32_16x16x32_bf16 v[36:39], v[170:173], v[196:199], v[36:39]
	v_mfma_f32_16x16x32_bf16 v[20:23], v[170:173], v[204:207], v[20:23]
	v_mfma_f32_16x16x32_bf16 v[16:19], v[180:183], v[204:207], v[16:19]
	v_mfma_f32_16x16x32_bf16 v[0:3], v[180:183], v[212:215], v[0:3]
	v_mfma_f32_16x16x32_bf16 v[4:7], v[170:173], v[212:215], v[4:7]
	v_mfma_f32_16x16x32_bf16 v[4:7], v[176:179], v[216:219], v[4:7]
	v_mfma_f32_16x16x32_bf16 v[0:3], v[184:187], v[216:219], v[0:3]
	v_mfma_f32_16x16x32_bf16 v[16:19], v[184:187], v[208:211], v[16:19]
	v_mfma_f32_16x16x32_bf16 v[20:23], v[176:179], v[208:211], v[20:23]
	v_mfma_f32_16x16x32_bf16 v[36:39], v[176:179], v[200:203], v[36:39]
	v_mfma_f32_16x16x32_bf16 v[32:35], v[184:187], v[200:203], v[32:35]
	v_mfma_f32_16x16x32_bf16 v[48:51], v[184:187], v[192:195], v[48:51]
	v_mfma_f32_16x16x32_bf16 v[52:55], v[176:179], v[192:195], v[52:55]
	s_setprio 0
	s_add_i32 s65, s65, 2
	s_add_u32 s42, s42, 0x100
	s_addc_u32 s43, s43, 0
	s_add_u32 s63, s63, 0x100
	s_addc_u32 s64, s64, 0
	s_cmp_gt_u32 s65, 29
	s_cbranch_scc0 .Lp7_kloop_h1
